# diff attention: wave-level test skips the cross-quad max reduction and rescale factor when no row can exceed the rescale threshold
# speedup vs baseline: 1.0304x; 1.0020x over previous
.LBB0_1310:
	s_mov_b32 s10, s2
	s_add_i32 s10, s45, s10
	s_add_i32 s2, s2, 1
	s_add_i32 s10, s10, 33
	s_cmp_lt_u32 s2, s36
	s_cselect_b32 s11, s2, s10
	s_lshl_b32 s10, s11, 6
	s_cmp_lt_i32 s11, 32
	s_cselect_b32 s11, s8, s9
	s_add_i32 s11, s11, s10
	v_add_u32_e32 v2, s11, v150
	v_mad_i64_i32 v[2:3], s[20:21], v2, s6, v[130:131]
	s_barrier
	s_waitcnt vmcnt(5)
	ds_write_b128 v154, v[84:87]
	s_waitcnt vmcnt(4)
	ds_write_b128 v155, v[88:91]
	s_waitcnt vmcnt(3)
	ds_write_b128 v154, v[92:95] offset:9216
	s_waitcnt vmcnt(2)
	ds_write_b128 v155, v[96:99] offset:9216
	s_waitcnt vmcnt(1)
	ds_write_b128 v156, v[100:103] offset:9216
	s_waitcnt vmcnt(0)
	ds_write_b128 v157, v[104:107] offset:9216
	s_waitcnt lgkmcnt(0)
	s_barrier
	global_load_dwordx4 v[84:87], v[2:3], off
	v_add_u32_e32 v2, s11, v151
	s_ashr_i32 s11, s10, 31
	v_mad_i64_i32 v[2:3], s[20:21], v2, s6, v[130:131]
	s_lshl_b64 s[10:11], s[10:11], 1
	global_load_dwordx4 v[88:91], v[2:3], off
	v_lshl_add_u64 v[2:3], v[132:133], 0, s[10:11]
	global_load_dwordx4 v[92:95], v[2:3], off
	v_lshl_add_u64 v[2:3], v[134:135], 0, s[10:11]
	global_load_dwordx4 v[96:99], v[2:3], off
	v_lshl_add_u64 v[2:3], v[136:137], 0, s[10:11]
	global_load_dwordx4 v[100:103], v[2:3], off
	v_lshl_add_u64 v[2:3], v[138:139], 0, s[10:11]
	global_load_dwordx4 v[104:107], v[2:3], off
	v_add_u32_e32 v2, v152, v153
	ds_read_b128 v[108:111], v2
	ds_read_b128 v[116:119], v2 offset:64
	s_waitcnt lgkmcnt(1)
	v_mfma_f32_16x16x32_bf16 v[112:115], v[108:111], v[72:75], 0
	ds_read_b128 v[120:123], v2 offset:2368
	ds_read_b128 v[166:169], v2 offset:4672
	v_mov_b32_e32 v174, v159
	s_waitcnt lgkmcnt(2)
	v_mfma_f32_16x16x32_bf16 v[124:127], v[116:119], v[68:71], v[112:115]
	ds_read_b128 v[170:173], v2 offset:6976
	s_nop 1
	ds_read_b128 v[112:115], v2 offset:2304
	v_mfma_f32_16x16x32_bf16 v[108:111], v[108:111], v[76:79], 0
	s_nop 2
	v_max3_f32 v3, v124, s76, v125
	v_max3_f32 v3, v3, v126, v127
	v_mfma_f32_16x16x32_bf16 v[108:111], v[116:119], v[80:83], v[108:111]
	s_waitcnt lgkmcnt(0)
	v_mfma_f32_16x16x32_bf16 v[116:119], v[112:115], v[72:75], 0
	v_mfma_f32_16x16x32_bf16 v[162:165], v[120:123], v[68:71], v[116:119]
	v_mfma_f32_16x16x32_bf16 v[112:115], v[112:115], v[76:79], 0
	s_nop 5
	ds_read_b128 v[116:119], v2 offset:4608
	v_max3_f32 v3, v3, v162, v163
	v_max3_f32 v3, v3, v164, v165
	v_mfma_f32_16x16x32_bf16 v[112:115], v[120:123], v[80:83], v[112:115]
	s_waitcnt lgkmcnt(0)
	v_mfma_f32_16x16x32_bf16 v[120:123], v[116:119], v[72:75], 0
	v_mfma_f32_16x16x32_bf16 v[176:179], v[166:169], v[68:71], v[120:123]
	s_nop 6
	ds_read_b128 v[120:123], v2 offset:6912
	v_mfma_f32_16x16x32_bf16 v[116:119], v[116:119], v[76:79], 0
	v_max3_f32 v3, v3, v176, v177
	v_max3_f32 v3, v3, v178, v179
	v_mfma_f32_16x16x32_bf16 v[116:119], v[166:169], v[80:83], v[116:119]
	s_waitcnt lgkmcnt(0)
	v_mfma_f32_16x16x32_bf16 v[166:169], v[120:123], v[72:75], 0
	v_mfma_f32_16x16x32_bf16 v[180:183], v[170:173], v[68:71], v[166:169]
	v_mfma_f32_16x16x32_bf16 v[120:123], v[120:123], v[76:79], 0
	v_mfma_f32_16x16x32_bf16 v[120:123], v[170:173], v[80:83], v[120:123]
	s_nop 5
	v_max3_f32 v3, v3, v180, v181
	v_max3_f32 v3, v3, v182, v183
	v_add_f32_e32 v184, 0x40b17218, v174
	v_cmp_gt_f32_e32 vcc, v3, v184
	s_cbranch_vccz .Lfm0_fast
	v_mov_b32_e32 v159, v3
	s_nop 1
	v_permlane16_swap_b32 v159, v3
	s_waitcnt lgkmcnt(0)
	v_max_f32_e32 v159, v159, v159
	v_max_f32_e32 v3, v3, v159
	v_mov_b32_e32 v159, v3
	s_nop 1
	v_permlane32_swap_b32 v159, v3
	s_waitcnt lgkmcnt(0)
	v_max3_f32 v159, v174, v3, v159
	v_sub_f32_e32 v3, v159, v174
	v_cmp_lt_f32_e32 vcc, 0x40b17218, v3
	s_nop 1
	v_cndmask_b32_e32 v159, v174, v159, vcc
	v_sub_f32_e32 v3, v174, v159
	v_mul_f32_e32 v3, 0x3fb8aa3b, v3
	v_exp_f32_e32 v169, v3
	s_branch .Lfm0_join
.Lfm0_fast:
	v_mov_b32_e32 v169, 1.0
.Lfm0_join:
	v_mul_f32_e32 v3, 0xbfb8aa3b, v159
	v_fmamk_f32 v124, v124, 0x3fb8aa3b, v3
	v_exp_f32_e32 v167, v124
	v_fmamk_f32 v125, v125, 0x3fb8aa3b, v3
	v_exp_f32_e32 v168, v125
	v_fmamk_f32 v125, v126, 0x3fb8aa3b, v3
	v_exp_f32_e32 v170, v125
	v_fmamk_f32 v125, v127, 0x3fb8aa3b, v3
	v_exp_f32_e32 v171, v125
	v_fmamk_f32 v125, v162, 0x3fb8aa3b, v3
	v_add_f32_e32 v124, 0, v167
	v_exp_f32_e32 v172, v125
	v_fmamk_f32 v125, v163, 0x3fb8aa3b, v3
	v_add_f32_e32 v124, v168, v124
	v_exp_f32_e32 v173, v125
	v_fmamk_f32 v125, v164, 0x3fb8aa3b, v3
	v_add_f32_e32 v124, v170, v124
	v_exp_f32_e32 v174, v125
	v_fmamk_f32 v125, v165, 0x3fb8aa3b, v3
	v_add_f32_e32 v124, v171, v124
	v_exp_f32_e32 v175, v125
	v_fmamk_f32 v125, v176, 0x3fb8aa3b, v3
	v_add_f32_e32 v124, v172, v124
	v_exp_f32_e32 v125, v125
	v_fmamk_f32 v126, v177, 0x3fb8aa3b, v3
	v_add_f32_e32 v124, v173, v124
	v_exp_f32_e32 v126, v126
	v_fmamk_f32 v127, v178, 0x3fb8aa3b, v3
	v_add_f32_e32 v124, v174, v124
	v_exp_f32_e32 v127, v127
	v_fmamk_f32 v162, v179, 0x3fb8aa3b, v3
	v_add_f32_e32 v124, v175, v124
	v_exp_f32_e32 v162, v162
	v_fmamk_f32 v163, v180, 0x3fb8aa3b, v3
	v_add_f32_e32 v124, v125, v124
	v_exp_f32_e32 v163, v163
	v_fmamk_f32 v164, v181, 0x3fb8aa3b, v3
	v_add_f32_e32 v124, v126, v124
	v_exp_f32_e32 v164, v164
	v_fmamk_f32 v165, v182, 0x3fb8aa3b, v3
	v_add_f32_e32 v124, v127, v124
	v_exp_f32_e32 v165, v165
	v_fmac_f32_e32 v3, 0x3fb8aa3b, v183
	v_add_f32_e32 v124, v162, v124
	v_exp_f32_e32 v166, v3
	v_add_f32_e32 v124, v163, v124
	v_add_f32_e32 v124, v164, v124
	v_add_f32_e32 v124, v165, v124
	v_add_f32_e32 v3, v166, v124
	v_cmp_neq_f32_e32 vcc, 1.0, v169
	s_waitcnt lgkmcnt(0)
	s_cbranch_vccz .LBB0_1312
	ds_bpermute_b32 v178, v146, v169
	ds_bpermute_b32 v180, v144, v169
	ds_bpermute_b32 v181, v145, v169
	ds_bpermute_b32 v179, v147, v169
	s_waitcnt lgkmcnt(1)
	v_pk_mul_f32 v[66:67], v[66:67], v[180:181]
	s_waitcnt lgkmcnt(0)
	v_pk_mul_f32 v[64:65], v[64:65], v[178:179]
	v_pk_mul_f32 v[58:59], v[58:59], v[180:181]
	v_pk_mul_f32 v[56:57], v[56:57], v[178:179]
	v_pk_mul_f32 v[50:51], v[50:51], v[180:181]
	v_pk_mul_f32 v[48:49], v[48:49], v[178:179]
	v_pk_mul_f32 v[42:43], v[42:43], v[180:181]
	v_pk_mul_f32 v[40:41], v[40:41], v[178:179]
	v_pk_mul_f32 v[34:35], v[34:35], v[180:181]
	v_pk_mul_f32 v[32:33], v[32:33], v[178:179]
	v_pk_mul_f32 v[26:27], v[26:27], v[180:181]
	v_pk_mul_f32 v[24:25], v[24:25], v[178:179]
	v_pk_mul_f32 v[18:19], v[18:19], v[180:181]
	v_pk_mul_f32 v[16:17], v[16:17], v[178:179]
	v_pk_mul_f32 v[14:15], v[14:15], v[180:181]
	v_pk_mul_f32 v[12:13], v[12:13], v[178:179]
.LBB0_1312:
	v_max3_f32 v124, v108, s76, v109
	v_max3_f32 v124, v124, v110, v111
	v_max3_f32 v124, v124, v112, v113
	v_max3_f32 v124, v124, v114, v115
	v_max3_f32 v124, v124, v116, v117
	v_max3_f32 v124, v124, v118, v119
	v_max3_f32 v124, v124, v120, v121
	v_max3_f32 v124, v124, v122, v123
	v_add_f32_e32 v184, 0x40b17218, v161
	v_cmp_gt_f32_e32 vcc, v124, v184
	s_cbranch_vccz .Lfm1_fast
	v_mov_b32_e32 v177, v124
	s_nop 1
	v_permlane16_swap_b32 v177, v124
	s_waitcnt lgkmcnt(0)
	v_max_f32_e32 v177, v177, v177
	v_max_f32_e32 v124, v124, v177
	v_mov_b32_e32 v177, v124
	s_nop 1
	v_permlane32_swap_b32 v177, v124
	s_waitcnt lgkmcnt(0)
	v_max3_f32 v124, v161, v124, v177
	v_sub_f32_e32 v177, v124, v161
	v_cmp_lt_f32_e32 vcc, 0x40b17218, v177
	s_nop 1
	v_cndmask_b32_e32 v124, v161, v124, vcc
	s_branch .Lfm1_join
.Lfm1_fast:
	v_mov_b32_e32 v124, v161
.Lfm1_join:
	v_mul_f32_e32 v178, 0xbfb8aa3b, v124
	v_fmamk_f32 v108, v108, 0x3fb8aa3b, v178
	v_fmamk_f32 v109, v109, 0x3fb8aa3b, v178
	v_exp_f32_e32 v108, v108
	v_fmamk_f32 v110, v110, 0x3fb8aa3b, v178
	v_exp_f32_e32 v109, v109
	v_fmamk_f32 v111, v111, 0x3fb8aa3b, v178
	v_exp_f32_e32 v110, v110
	v_fmamk_f32 v112, v112, 0x3fb8aa3b, v178
	v_exp_f32_e32 v111, v111
	v_fmamk_f32 v113, v113, 0x3fb8aa3b, v178
	v_exp_f32_e32 v112, v112
	v_add_f32_e32 v177, 0, v108
	v_fmamk_f32 v114, v114, 0x3fb8aa3b, v178
	v_exp_f32_e32 v113, v113
	v_add_f32_e32 v177, v109, v177
	v_add_f32_e32 v177, v110, v177
	v_exp_f32_e32 v114, v114
	v_fmamk_f32 v115, v115, 0x3fb8aa3b, v178
	v_add_f32_e32 v179, v111, v177
	v_exp_f32_e32 v177, v115
	v_fmamk_f32 v116, v116, 0x3fb8aa3b, v178
	v_add_f32_e32 v115, v112, v179
	v_exp_f32_e32 v116, v116
	v_fmamk_f32 v117, v117, 0x3fb8aa3b, v178
	v_add_f32_e32 v115, v113, v115
	v_exp_f32_e32 v117, v117
	v_fmamk_f32 v118, v118, 0x3fb8aa3b, v178
	v_add_f32_e32 v115, v114, v115
	v_exp_f32_e32 v118, v118
	v_fmamk_f32 v119, v119, 0x3fb8aa3b, v178
	v_add_f32_e32 v115, v177, v115
	v_exp_f32_e32 v119, v119
	v_fmamk_f32 v120, v120, 0x3fb8aa3b, v178
	v_add_f32_e32 v115, v116, v115
	v_exp_f32_e32 v120, v120
	v_fmamk_f32 v121, v121, 0x3fb8aa3b, v178
	v_add_f32_e32 v115, v117, v115
	v_exp_f32_e32 v121, v121
	v_fmamk_f32 v122, v122, 0x3fb8aa3b, v178
	v_add_f32_e32 v115, v118, v115
	v_exp_f32_e32 v122, v122
	v_fmac_f32_e32 v178, 0x3fb8aa3b, v123
	v_add_f32_e32 v115, v119, v115
	v_exp_f32_e32 v123, v178
	v_add_f32_e32 v115, v120, v115
	v_add_f32_e32 v115, v121, v115
	v_add_f32_e32 v115, v122, v115
	v_add_f32_e32 v115, v123, v115
	v_sub_f32_e32 v161, v161, v124
	v_mul_f32_e32 v161, 0x3fb8aa3b, v161
	v_exp_f32_e32 v161, v161
	s_waitcnt lgkmcnt(0)
	v_cmp_neq_f32_e32 vcc, 1.0, v161
	s_cbranch_vccz .LBB0_1314
	ds_bpermute_b32 v180, v146, v161
	ds_bpermute_b32 v182, v144, v161
	ds_bpermute_b32 v183, v145, v161
	ds_bpermute_b32 v181, v147, v161
	s_waitcnt lgkmcnt(1)
	v_pk_mul_f32 v[62:63], v[62:63], v[182:183]
	s_waitcnt lgkmcnt(0)
	v_pk_mul_f32 v[60:61], v[60:61], v[180:181]
	v_pk_mul_f32 v[54:55], v[54:55], v[182:183]
	v_pk_mul_f32 v[52:53], v[52:53], v[180:181]
	v_pk_mul_f32 v[46:47], v[46:47], v[182:183]
	v_pk_mul_f32 v[44:45], v[44:45], v[180:181]
	v_pk_mul_f32 v[38:39], v[38:39], v[182:183]
	v_pk_mul_f32 v[36:37], v[36:37], v[180:181]
	v_pk_mul_f32 v[30:31], v[30:31], v[182:183]
	v_pk_mul_f32 v[28:29], v[28:29], v[180:181]
	v_pk_mul_f32 v[22:23], v[22:23], v[182:183]
	v_pk_mul_f32 v[20:21], v[20:21], v[180:181]
	v_pk_mul_f32 v[10:11], v[10:11], v[182:183]
	v_pk_mul_f32 v[8:9], v[8:9], v[180:181]
	v_pk_mul_f32 v[6:7], v[6:7], v[182:183]
	v_pk_mul_f32 v[4:5], v[4:5], v[180:181]
